# h1 no longer stored: phase 10 recomputes x + rmsnorm(o0)*post0 (o1 now written to the dead CAT0 region so o0 survives); saves 68 MB of f32 writes
# speedup vs baseline: 1.0428x; 1.0082x over previous
.LBB0_77:
	s_lshl_b32 s2, s47, 3
	s_mov_b32 s0, s2
	s_waitcnt vmcnt(0)
	v_lshrrev_b32_e32 v9, 6, v49
	v_writelane_b32 v252, s0, 40
	s_lshl_b32 s50, s46, 3
	v_writelane_b32 v252, s1, 41
	v_mbcnt_lo_u32_b32 v209, -1, 0
	v_and_b32_e32 v10, 63, v49
	v_readlane_b32 s16, v252, 14
	v_readlane_b32 s17, v252, 15
	v_readlane_b32 s18, v252, 18
	v_readlane_b32 s19, v252, 19
	v_readfirstlane_b32 s3, v9
	v_lshlrev_b32_e32 v0, 4, v10
	v_lshlrev_b32_e32 v1, 3, v10
	v_add_u32_e32 v124, 0x1000, v0
	v_lshlrev_b32_e32 v11, 2, v10
	v_xor_b32_e32 v2, 0x80, v11
	v_xor_b32_e32 v3, 64, v11
	v_xor_b32_e32 v4, 32, v11
	v_xor_b32_e32 v5, 16, v11
	v_xor_b32_e32 v6, 8, v11
	v_xor_b32_e32 v7, 4, v11
	v_mov_b32_e32 v8, 0x358637bd
	v_mov_b32_e32 v122, 0
	v_mov_b32_e32 v123, 0
	s_add_i32 s2, s2, s3
	s_mov_b32 s3, s50
	s_mov_b32 s10, 0
	s_mov_b64 s[76:77], s[16:17]
	s_waitcnt lgkmcnt(0)
	s_mov_b64 s[98:99], s[60:61]
	s_mov_b64 s[100:101], s[62:63]
	global_load_dwordx4 v[12:15], v0, s[76:77]
	global_load_dwordx4 v[16:19], v0, s[76:77] offset:1024
	global_load_dwordx4 v[20:23], v0, s[76:77] offset:2048
	global_load_dwordx4 v[24:27], v0, s[76:77] offset:3072
	global_load_dwordx4 v[28:31], v124, s[76:77]
	global_load_dwordx4 v[32:35], v124, s[76:77] offset:1024
	global_load_dwordx4 v[36:39], v124, s[76:77] offset:2048
	global_load_dwordx4 v[40:43], v124, s[76:77] offset:3072

.Lp6_A:
	s_waitcnt vmcnt(4)

.Lp6_A_nopf:
	s_lshl_b32 s4, s2, 12
	s_add_u32 s16, s26, s4
	s_addc_u32 s17, s27, 0
	s_lshl_b32 s4, s2, 13
	s_add_u32 s14, s22, s4
	s_addc_u32 s15, s23, 0
	v_lshlrev_b32_e32 v172, 16, v76
	v_and_b32_e32 v173, 0xffff0000, v76
	v_lshlrev_b32_e32 v174, 16, v77
	v_and_b32_e32 v175, 0xffff0000, v77
	v_lshlrev_b32_e32 v176, 16, v78
	v_and_b32_e32 v177, 0xffff0000, v78
	v_lshlrev_b32_e32 v178, 16, v79
	v_and_b32_e32 v179, 0xffff0000, v79
	v_lshlrev_b32_e32 v180, 16, v80
	v_and_b32_e32 v181, 0xffff0000, v80
	v_lshlrev_b32_e32 v182, 16, v81
	v_and_b32_e32 v183, 0xffff0000, v81
	v_lshlrev_b32_e32 v184, 16, v82
	v_and_b32_e32 v185, 0xffff0000, v82
	v_lshlrev_b32_e32 v186, 16, v83
	v_and_b32_e32 v187, 0xffff0000, v83
	v_lshlrev_b32_e32 v188, 16, v84
	v_and_b32_e32 v189, 0xffff0000, v84
	v_lshlrev_b32_e32 v190, 16, v85
	v_and_b32_e32 v191, 0xffff0000, v85
	v_lshlrev_b32_e32 v192, 16, v86
	v_and_b32_e32 v193, 0xffff0000, v86
	v_lshlrev_b32_e32 v194, 16, v87
	v_and_b32_e32 v195, 0xffff0000, v87
	v_lshlrev_b32_e32 v196, 16, v88
	v_and_b32_e32 v197, 0xffff0000, v88
	v_lshlrev_b32_e32 v198, 16, v89
	v_and_b32_e32 v199, 0xffff0000, v89
	v_lshlrev_b32_e32 v200, 16, v90
	v_and_b32_e32 v201, 0xffff0000, v90
	v_lshlrev_b32_e32 v202, 16, v91
	v_and_b32_e32 v203, 0xffff0000, v91
	v_mul_f32_e32 v206, v172, v172
	v_mul_f32_e32 v207, v173, v173
	v_mul_f32_e32 v210, v174, v174
	v_mul_f32_e32 v211, v175, v175
	v_fmac_f32_e32 v206, v176, v176
	v_fmac_f32_e32 v207, v177, v177
	v_fmac_f32_e32 v210, v178, v178
	v_fmac_f32_e32 v211, v179, v179
	v_fmac_f32_e32 v206, v180, v180
	v_fmac_f32_e32 v207, v181, v181
	v_fmac_f32_e32 v210, v182, v182
	v_fmac_f32_e32 v211, v183, v183
	v_fmac_f32_e32 v206, v184, v184
	v_fmac_f32_e32 v207, v185, v185
	v_fmac_f32_e32 v210, v186, v186
	v_fmac_f32_e32 v211, v187, v187
	v_fmac_f32_e32 v206, v188, v188
	v_fmac_f32_e32 v207, v189, v189
	v_fmac_f32_e32 v210, v190, v190
	v_fmac_f32_e32 v211, v191, v191
	v_fmac_f32_e32 v206, v192, v192
	v_fmac_f32_e32 v207, v193, v193
	v_fmac_f32_e32 v210, v194, v194
	v_fmac_f32_e32 v211, v195, v195
	v_fmac_f32_e32 v206, v196, v196
	v_fmac_f32_e32 v207, v197, v197
	v_fmac_f32_e32 v210, v198, v198
	v_fmac_f32_e32 v211, v199, v199
	v_fmac_f32_e32 v206, v200, v200
	v_fmac_f32_e32 v207, v201, v201
	v_fmac_f32_e32 v210, v202, v202
	v_fmac_f32_e32 v211, v203, v203
	v_add_f32_e32 v206, v206, v207
	v_add_f32_e32 v210, v210, v211
	v_add_f32_e32 v206, v206, v210
	ds_bpermute_b32 v212, v7, v206
	s_waitcnt lgkmcnt(0)
	v_add_f32_e32 v206, v206, v212
	ds_bpermute_b32 v212, v8, v206
	s_waitcnt lgkmcnt(0)
	v_add_f32_e32 v206, v206, v212
	ds_bpermute_b32 v212, v9, v206
	s_waitcnt lgkmcnt(0)
	v_add_f32_e32 v206, v206, v212
	ds_bpermute_b32 v212, v10, v206
	s_waitcnt lgkmcnt(0)
	v_add_f32_e32 v206, v206, v212
	ds_bpermute_b32 v212, v11, v206
	s_waitcnt lgkmcnt(0)
	v_add_f32_e32 v206, v206, v212
	ds_bpermute_b32 v212, v204, v206
	s_waitcnt lgkmcnt(0)
	v_add_f32_e32 v206, v206, v212
	v_fmamk_f32 v206, v206, 0x3a000000, v205
	v_rsq_f32_e32 v213, v206
	s_nop 0
	v_mul_f32_e32 v172, v172, v213
	v_fmac_f32_e32 v92, v172, v12
	v_mul_f32_e32 v173, v173, v213
	v_fmac_f32_e32 v93, v173, v13
	v_mul_f32_e32 v174, v174, v213
	v_fmac_f32_e32 v94, v174, v14
	v_mul_f32_e32 v175, v175, v213
	v_fmac_f32_e32 v95, v175, v15
	v_mul_f32_e32 v176, v176, v213
	v_fmac_f32_e32 v96, v176, v16
	v_mul_f32_e32 v177, v177, v213
	v_fmac_f32_e32 v97, v177, v17
	v_mul_f32_e32 v178, v178, v213
	v_fmac_f32_e32 v98, v178, v18
	v_mul_f32_e32 v179, v179, v213
	v_fmac_f32_e32 v99, v179, v19
	v_mul_f32_e32 v180, v180, v213
	v_fmac_f32_e32 v100, v180, v20
	v_mul_f32_e32 v181, v181, v213
	v_fmac_f32_e32 v101, v181, v21
	v_mul_f32_e32 v182, v182, v213
	v_fmac_f32_e32 v102, v182, v22
	v_mul_f32_e32 v183, v183, v213
	v_fmac_f32_e32 v103, v183, v23
	v_mul_f32_e32 v184, v184, v213
	v_fmac_f32_e32 v104, v184, v24
	v_mul_f32_e32 v185, v185, v213
	v_fmac_f32_e32 v105, v185, v25
	v_mul_f32_e32 v186, v186, v213
	v_fmac_f32_e32 v106, v186, v26
	v_mul_f32_e32 v187, v187, v213
	v_fmac_f32_e32 v107, v187, v27
	v_mul_f32_e32 v188, v188, v213
	v_fmac_f32_e32 v108, v188, v28
	v_mul_f32_e32 v189, v189, v213
	v_fmac_f32_e32 v109, v189, v29
	v_mul_f32_e32 v190, v190, v213
	v_fmac_f32_e32 v110, v190, v30
	v_mul_f32_e32 v191, v191, v213
	v_fmac_f32_e32 v111, v191, v31
	v_mul_f32_e32 v192, v192, v213
	v_fmac_f32_e32 v112, v192, v32
	v_mul_f32_e32 v193, v193, v213
	v_fmac_f32_e32 v113, v193, v33
	v_mul_f32_e32 v194, v194, v213
	v_fmac_f32_e32 v114, v194, v34
	v_mul_f32_e32 v195, v195, v213
	v_fmac_f32_e32 v115, v195, v35
	v_mul_f32_e32 v196, v196, v213
	v_fmac_f32_e32 v116, v196, v36
	v_mul_f32_e32 v197, v197, v213
	v_fmac_f32_e32 v117, v197, v37
	v_mul_f32_e32 v198, v198, v213
	v_fmac_f32_e32 v118, v198, v38
	v_mul_f32_e32 v199, v199, v213
	v_fmac_f32_e32 v119, v199, v39
	v_mul_f32_e32 v200, v200, v213
	v_fmac_f32_e32 v120, v200, v40
	v_mul_f32_e32 v201, v201, v213
	v_fmac_f32_e32 v121, v201, v41
	v_mul_f32_e32 v202, v202, v213
	v_fmac_f32_e32 v122, v202, v42
	v_mul_f32_e32 v203, v203, v213
	v_fmac_f32_e32 v123, v203, v43
	v_mul_f32_e32 v206, v92, v92
	v_mul_f32_e32 v207, v93, v93
	v_mul_f32_e32 v210, v94, v94
	v_mul_f32_e32 v211, v95, v95
	v_fmac_f32_e32 v206, v96, v96
	v_fmac_f32_e32 v207, v97, v97
	v_fmac_f32_e32 v210, v98, v98
	v_fmac_f32_e32 v211, v99, v99
	v_fmac_f32_e32 v206, v100, v100
	v_fmac_f32_e32 v207, v101, v101
	v_fmac_f32_e32 v210, v102, v102
	v_fmac_f32_e32 v211, v103, v103
	v_fmac_f32_e32 v206, v104, v104
	v_fmac_f32_e32 v207, v105, v105
	v_fmac_f32_e32 v210, v106, v106
	v_fmac_f32_e32 v211, v107, v107
	v_fmac_f32_e32 v206, v108, v108
	v_fmac_f32_e32 v207, v109, v109
	v_fmac_f32_e32 v210, v110, v110
	v_fmac_f32_e32 v211, v111, v111
	v_fmac_f32_e32 v206, v112, v112
	v_fmac_f32_e32 v207, v113, v113
	v_fmac_f32_e32 v210, v114, v114
	v_fmac_f32_e32 v211, v115, v115
	v_fmac_f32_e32 v206, v116, v116
	v_fmac_f32_e32 v207, v117, v117
	v_fmac_f32_e32 v210, v118, v118
	v_fmac_f32_e32 v211, v119, v119
	v_fmac_f32_e32 v206, v120, v120
	v_fmac_f32_e32 v207, v121, v121
	v_fmac_f32_e32 v210, v122, v122
	v_fmac_f32_e32 v211, v123, v123
	v_add_f32_e32 v206, v206, v207
	v_add_f32_e32 v210, v210, v211
	v_add_f32_e32 v206, v206, v210
	ds_bpermute_b32 v212, v7, v206
	s_waitcnt lgkmcnt(0)
	v_add_f32_e32 v206, v206, v212
	ds_bpermute_b32 v212, v8, v206
	s_waitcnt lgkmcnt(0)
	v_add_f32_e32 v206, v206, v212
	ds_bpermute_b32 v212, v9, v206
	s_waitcnt lgkmcnt(0)
	v_add_f32_e32 v206, v206, v212
	ds_bpermute_b32 v212, v10, v206
	s_waitcnt lgkmcnt(0)
	v_add_f32_e32 v206, v206, v212
	ds_bpermute_b32 v212, v11, v206
	s_waitcnt lgkmcnt(0)
	v_add_f32_e32 v206, v206, v212
	ds_bpermute_b32 v212, v204, v206
	s_waitcnt lgkmcnt(0)
	v_add_f32_e32 v206, v206, v212
	v_fmamk_f32 v206, v206, 0x3a000000, v205
	v_rsq_f32_e32 v213, v206
	s_nop 0
	v_mul_f32_e32 v172, v92, v213
	v_mul_f32_e32 v172, v172, v44
	v_mul_f32_e32 v173, v93, v213
	v_mul_f32_e32 v173, v173, v45
	v_mul_f32_e32 v174, v94, v213
	v_mul_f32_e32 v174, v174, v46
	v_mul_f32_e32 v175, v95, v213
	v_mul_f32_e32 v175, v175, v47
	v_mul_f32_e32 v176, v96, v213
	v_mul_f32_e32 v176, v176, v48
	v_mul_f32_e32 v177, v97, v213
	v_mul_f32_e32 v177, v177, v49
	v_mul_f32_e32 v178, v98, v213
	v_mul_f32_e32 v178, v178, v50
	v_mul_f32_e32 v179, v99, v213
	v_mul_f32_e32 v179, v179, v51
	v_mul_f32_e32 v180, v100, v213
	v_mul_f32_e32 v180, v180, v52
	v_mul_f32_e32 v181, v101, v213
	v_mul_f32_e32 v181, v181, v53
	v_mul_f32_e32 v182, v102, v213
	v_mul_f32_e32 v182, v182, v54
	v_mul_f32_e32 v183, v103, v213
	v_mul_f32_e32 v183, v183, v55
	v_mul_f32_e32 v184, v104, v213
	v_mul_f32_e32 v184, v184, v56
	v_mul_f32_e32 v185, v105, v213
	v_mul_f32_e32 v185, v185, v57
	v_mul_f32_e32 v186, v106, v213
	v_mul_f32_e32 v186, v186, v58
	v_mul_f32_e32 v187, v107, v213
	v_mul_f32_e32 v187, v187, v59
	v_mul_f32_e32 v188, v108, v213
	v_mul_f32_e32 v188, v188, v60
	v_mul_f32_e32 v189, v109, v213
	v_mul_f32_e32 v189, v189, v61
	v_mul_f32_e32 v190, v110, v213
	v_mul_f32_e32 v190, v190, v62
	v_mul_f32_e32 v191, v111, v213
	v_mul_f32_e32 v191, v191, v63
	v_mul_f32_e32 v192, v112, v213
	v_mul_f32_e32 v192, v192, v64
	v_mul_f32_e32 v193, v113, v213
	v_mul_f32_e32 v193, v193, v65
	v_mul_f32_e32 v194, v114, v213
	v_mul_f32_e32 v194, v194, v66
	v_mul_f32_e32 v195, v115, v213
	v_mul_f32_e32 v195, v195, v67
	v_mul_f32_e32 v196, v116, v213
	v_mul_f32_e32 v196, v196, v68
	v_mul_f32_e32 v197, v117, v213
	v_mul_f32_e32 v197, v197, v69
	v_mul_f32_e32 v198, v118, v213
	v_mul_f32_e32 v198, v198, v70
	v_mul_f32_e32 v199, v119, v213
	v_mul_f32_e32 v199, v199, v71
	v_mul_f32_e32 v200, v120, v213
	v_mul_f32_e32 v200, v200, v72
	v_mul_f32_e32 v201, v121, v213
	v_mul_f32_e32 v201, v201, v73
	v_mul_f32_e32 v202, v122, v213
	v_mul_f32_e32 v202, v202, v74
	v_mul_f32_e32 v203, v123, v213
	v_mul_f32_e32 v203, v203, v75
	v_cvt_pk_bf16_f32 v76, v172, v173
	v_cvt_pk_bf16_f32 v77, v174, v175
	v_cvt_pk_bf16_f32 v78, v176, v177
	v_cvt_pk_bf16_f32 v79, v178, v179
	v_cvt_pk_bf16_f32 v80, v180, v181
	v_cvt_pk_bf16_f32 v81, v182, v183
	v_cvt_pk_bf16_f32 v82, v184, v185
	v_cvt_pk_bf16_f32 v83, v186, v187
	v_cvt_pk_bf16_f32 v84, v188, v189
	v_cvt_pk_bf16_f32 v85, v190, v191
	v_cvt_pk_bf16_f32 v86, v192, v193
	v_cvt_pk_bf16_f32 v87, v194, v195
	v_cvt_pk_bf16_f32 v88, v196, v197
	v_cvt_pk_bf16_f32 v89, v198, v199
	v_cvt_pk_bf16_f32 v90, v200, v201
	v_cvt_pk_bf16_f32 v91, v202, v203
	global_store_dwordx4 v0, v[76:79], s[16:17]
	global_store_dwordx4 v0, v[80:83], s[16:17] offset:1024
	global_store_dwordx4 v0, v[84:87], s[16:17] offset:2048
	global_store_dwordx4 v0, v[88:91], s[16:17] offset:3072
	s_mov_b32 s2, s29
	s_cmp_ge_u32 s2, 0x2080
	s_cbranch_scc1 .Lp6_tail
.Lp6_B:
	s_waitcnt vmcnt(4)
	s_add_u32 s29, s2, s3
	s_cmp_ge_u32 s29, 0x2080
	s_cbranch_scc1 .Lp6_B_nopf
	s_lshl_b32 s4, s29, 12
	s_add_u32 s6, s24, s4
	s_addc_u32 s7, s25, 0
	s_lshl_b32 s4, s29, 13
	s_cmp_lt_u32 s29, 0x2000
	s_cselect_b32 s8, s60, s62
	s_cselect_b32 s9, s61, s63
	s_cselect_b32 s28, 0, 0x4000000
	s_sub_u32 s4, s4, s28
	s_add_u32 s8, s8, s4
	s_addc_u32 s9, s9, 0
	global_load_dwordx4 v[76:79], v0, s[6:7]
	global_load_dwordx4 v[80:83], v0, s[6:7] offset:1024
	global_load_dwordx4 v[84:87], v0, s[6:7] offset:2048
	global_load_dwordx4 v[88:91], v0, s[6:7] offset:3072
	global_load_dwordx4 v[92:95], v1, s[8:9]
	global_load_dwordx4 v[96:99], v1, s[8:9] offset:16
	global_load_dwordx4 v[100:103], v1, s[8:9] offset:2048
	global_load_dwordx4 v[104:107], v1, s[8:9] offset:2064
	global_load_dwordx4 v[108:111], v2, s[8:9]
	global_load_dwordx4 v[112:115], v2, s[8:9] offset:16
	global_load_dwordx4 v[116:119], v2, s[8:9] offset:2048
	global_load_dwordx4 v[120:123], v2, s[8:9] offset:2064
.Lp6_B_nopf:
	s_lshl_b32 s4, s2, 12
	s_add_u32 s16, s26, s4
	s_addc_u32 s17, s27, 0
	s_lshl_b32 s4, s2, 13
	s_add_u32 s14, s22, s4
	s_addc_u32 s15, s23, 0
	v_lshlrev_b32_e32 v172, 16, v124
	v_and_b32_e32 v173, 0xffff0000, v124
	v_lshlrev_b32_e32 v174, 16, v125
	v_and_b32_e32 v175, 0xffff0000, v125
	v_lshlrev_b32_e32 v176, 16, v126
	v_and_b32_e32 v177, 0xffff0000, v126
	v_lshlrev_b32_e32 v178, 16, v127
	v_and_b32_e32 v179, 0xffff0000, v127
	v_lshlrev_b32_e32 v180, 16, v128
	v_and_b32_e32 v181, 0xffff0000, v128
	v_lshlrev_b32_e32 v182, 16, v129
	v_and_b32_e32 v183, 0xffff0000, v129
	v_lshlrev_b32_e32 v184, 16, v130
	v_and_b32_e32 v185, 0xffff0000, v130
	v_lshlrev_b32_e32 v186, 16, v131
	v_and_b32_e32 v187, 0xffff0000, v131
	v_lshlrev_b32_e32 v188, 16, v132
	v_and_b32_e32 v189, 0xffff0000, v132
	v_lshlrev_b32_e32 v190, 16, v133
	v_and_b32_e32 v191, 0xffff0000, v133
	v_lshlrev_b32_e32 v192, 16, v134
	v_and_b32_e32 v193, 0xffff0000, v134
	v_lshlrev_b32_e32 v194, 16, v135
	v_and_b32_e32 v195, 0xffff0000, v135
	v_lshlrev_b32_e32 v196, 16, v136
	v_and_b32_e32 v197, 0xffff0000, v136
	v_lshlrev_b32_e32 v198, 16, v137
	v_and_b32_e32 v199, 0xffff0000, v137
	v_lshlrev_b32_e32 v200, 16, v138
	v_and_b32_e32 v201, 0xffff0000, v138
	v_lshlrev_b32_e32 v202, 16, v139
	v_and_b32_e32 v203, 0xffff0000, v139
	v_mul_f32_e32 v206, v172, v172
	v_mul_f32_e32 v207, v173, v173
	v_mul_f32_e32 v210, v174, v174
	v_mul_f32_e32 v211, v175, v175
	v_fmac_f32_e32 v206, v176, v176
	v_fmac_f32_e32 v207, v177, v177
	v_fmac_f32_e32 v210, v178, v178
	v_fmac_f32_e32 v211, v179, v179
	v_fmac_f32_e32 v206, v180, v180
	v_fmac_f32_e32 v207, v181, v181
	v_fmac_f32_e32 v210, v182, v182
	v_fmac_f32_e32 v211, v183, v183
	v_fmac_f32_e32 v206, v184, v184
	v_fmac_f32_e32 v207, v185, v185
	v_fmac_f32_e32 v210, v186, v186
	v_fmac_f32_e32 v211, v187, v187
	v_fmac_f32_e32 v206, v188, v188
	v_fmac_f32_e32 v207, v189, v189
	v_fmac_f32_e32 v210, v190, v190
	v_fmac_f32_e32 v211, v191, v191
	v_fmac_f32_e32 v206, v192, v192
	v_fmac_f32_e32 v207, v193, v193
	v_fmac_f32_e32 v210, v194, v194
	v_fmac_f32_e32 v211, v195, v195
	v_fmac_f32_e32 v206, v196, v196
	v_fmac_f32_e32 v207, v197, v197
	v_fmac_f32_e32 v210, v198, v198
	v_fmac_f32_e32 v211, v199, v199
	v_fmac_f32_e32 v206, v200, v200
	v_fmac_f32_e32 v207, v201, v201
	v_fmac_f32_e32 v210, v202, v202
	v_fmac_f32_e32 v211, v203, v203
	v_add_f32_e32 v206, v206, v207
	v_add_f32_e32 v210, v210, v211
	v_add_f32_e32 v206, v206, v210
	ds_bpermute_b32 v212, v7, v206
	s_waitcnt lgkmcnt(0)
	v_add_f32_e32 v206, v206, v212
	ds_bpermute_b32 v212, v8, v206
	s_waitcnt lgkmcnt(0)
	v_add_f32_e32 v206, v206, v212
	ds_bpermute_b32 v212, v9, v206
	s_waitcnt lgkmcnt(0)
	v_add_f32_e32 v206, v206, v212
	ds_bpermute_b32 v212, v10, v206
	s_waitcnt lgkmcnt(0)
	v_add_f32_e32 v206, v206, v212
	ds_bpermute_b32 v212, v11, v206
	s_waitcnt lgkmcnt(0)
	v_add_f32_e32 v206, v206, v212
	ds_bpermute_b32 v212, v204, v206
	s_waitcnt lgkmcnt(0)
	v_add_f32_e32 v206, v206, v212
	v_fmamk_f32 v206, v206, 0x3a000000, v205
	v_rsq_f32_e32 v213, v206
	s_nop 0
	v_mul_f32_e32 v172, v172, v213
	v_fmac_f32_e32 v140, v172, v12
	v_mul_f32_e32 v173, v173, v213
	v_fmac_f32_e32 v141, v173, v13
	v_mul_f32_e32 v174, v174, v213
	v_fmac_f32_e32 v142, v174, v14
	v_mul_f32_e32 v175, v175, v213
	v_fmac_f32_e32 v143, v175, v15
	v_mul_f32_e32 v176, v176, v213
	v_fmac_f32_e32 v144, v176, v16
	v_mul_f32_e32 v177, v177, v213
	v_fmac_f32_e32 v145, v177, v17
	v_mul_f32_e32 v178, v178, v213
	v_fmac_f32_e32 v146, v178, v18
	v_mul_f32_e32 v179, v179, v213
	v_fmac_f32_e32 v147, v179, v19
	v_mul_f32_e32 v180, v180, v213
	v_fmac_f32_e32 v148, v180, v20
	v_mul_f32_e32 v181, v181, v213
	v_fmac_f32_e32 v149, v181, v21
	v_mul_f32_e32 v182, v182, v213
	v_fmac_f32_e32 v150, v182, v22
	v_mul_f32_e32 v183, v183, v213
	v_fmac_f32_e32 v151, v183, v23
	v_mul_f32_e32 v184, v184, v213
	v_fmac_f32_e32 v152, v184, v24
	v_mul_f32_e32 v185, v185, v213
	v_fmac_f32_e32 v153, v185, v25
	v_mul_f32_e32 v186, v186, v213
	v_fmac_f32_e32 v154, v186, v26
	v_mul_f32_e32 v187, v187, v213
	v_fmac_f32_e32 v155, v187, v27
	v_mul_f32_e32 v188, v188, v213
	v_fmac_f32_e32 v156, v188, v28
	v_mul_f32_e32 v189, v189, v213
	v_fmac_f32_e32 v157, v189, v29
	v_mul_f32_e32 v190, v190, v213
	v_fmac_f32_e32 v158, v190, v30
	v_mul_f32_e32 v191, v191, v213
	v_fmac_f32_e32 v159, v191, v31
	v_mul_f32_e32 v192, v192, v213
	v_fmac_f32_e32 v160, v192, v32
	v_mul_f32_e32 v193, v193, v213
	v_fmac_f32_e32 v161, v193, v33
	v_mul_f32_e32 v194, v194, v213
	v_fmac_f32_e32 v162, v194, v34
	v_mul_f32_e32 v195, v195, v213
	v_fmac_f32_e32 v163, v195, v35
	v_mul_f32_e32 v196, v196, v213
	v_fmac_f32_e32 v164, v196, v36
	v_mul_f32_e32 v197, v197, v213
	v_fmac_f32_e32 v165, v197, v37
	v_mul_f32_e32 v198, v198, v213
	v_fmac_f32_e32 v166, v198, v38
	v_mul_f32_e32 v199, v199, v213
	v_fmac_f32_e32 v167, v199, v39
	v_mul_f32_e32 v200, v200, v213
	v_fmac_f32_e32 v168, v200, v40
	v_mul_f32_e32 v201, v201, v213
	v_fmac_f32_e32 v169, v201, v41
	v_mul_f32_e32 v202, v202, v213
	v_fmac_f32_e32 v170, v202, v42
	v_mul_f32_e32 v203, v203, v213
	v_fmac_f32_e32 v171, v203, v43
	v_mul_f32_e32 v206, v140, v140
	v_mul_f32_e32 v207, v141, v141
	v_mul_f32_e32 v210, v142, v142
	v_mul_f32_e32 v211, v143, v143
	v_fmac_f32_e32 v206, v144, v144
	v_fmac_f32_e32 v207, v145, v145
	v_fmac_f32_e32 v210, v146, v146
	v_fmac_f32_e32 v211, v147, v147
	v_fmac_f32_e32 v206, v148, v148
	v_fmac_f32_e32 v207, v149, v149
	v_fmac_f32_e32 v210, v150, v150
	v_fmac_f32_e32 v211, v151, v151
	v_fmac_f32_e32 v206, v152, v152
	v_fmac_f32_e32 v207, v153, v153
	v_fmac_f32_e32 v210, v154, v154
	v_fmac_f32_e32 v211, v155, v155
	v_fmac_f32_e32 v206, v156, v156
	v_fmac_f32_e32 v207, v157, v157
	v_fmac_f32_e32 v210, v158, v158
	v_fmac_f32_e32 v211, v159, v159
	v_fmac_f32_e32 v206, v160, v160
	v_fmac_f32_e32 v207, v161, v161
	v_fmac_f32_e32 v210, v162, v162
	v_fmac_f32_e32 v211, v163, v163
	v_fmac_f32_e32 v206, v164, v164
	v_fmac_f32_e32 v207, v165, v165
	v_fmac_f32_e32 v210, v166, v166
	v_fmac_f32_e32 v211, v167, v167
	v_fmac_f32_e32 v206, v168, v168
	v_fmac_f32_e32 v207, v169, v169
	v_fmac_f32_e32 v210, v170, v170
	v_fmac_f32_e32 v211, v171, v171
	v_add_f32_e32 v206, v206, v207
	v_add_f32_e32 v210, v210, v211
	v_add_f32_e32 v206, v206, v210
	ds_bpermute_b32 v212, v7, v206
	s_waitcnt lgkmcnt(0)
	v_add_f32_e32 v206, v206, v212
	ds_bpermute_b32 v212, v8, v206
	s_waitcnt lgkmcnt(0)
	v_add_f32_e32 v206, v206, v212
	ds_bpermute_b32 v212, v9, v206
	s_waitcnt lgkmcnt(0)
	v_add_f32_e32 v206, v206, v212
	ds_bpermute_b32 v212, v10, v206
	s_waitcnt lgkmcnt(0)
	v_add_f32_e32 v206, v206, v212
	ds_bpermute_b32 v212, v11, v206
	s_waitcnt lgkmcnt(0)
	v_add_f32_e32 v206, v206, v212
	ds_bpermute_b32 v212, v204, v206
	s_waitcnt lgkmcnt(0)
	v_add_f32_e32 v206, v206, v212
	v_fmamk_f32 v206, v206, 0x3a000000, v205
	v_rsq_f32_e32 v213, v206
	s_nop 0
	v_mul_f32_e32 v172, v140, v213
	v_mul_f32_e32 v172, v172, v44
	v_mul_f32_e32 v173, v141, v213
	v_mul_f32_e32 v173, v173, v45
	v_mul_f32_e32 v174, v142, v213
	v_mul_f32_e32 v174, v174, v46
	v_mul_f32_e32 v175, v143, v213
	v_mul_f32_e32 v175, v175, v47
	v_mul_f32_e32 v176, v144, v213
	v_mul_f32_e32 v176, v176, v48
	v_mul_f32_e32 v177, v145, v213
	v_mul_f32_e32 v177, v177, v49
	v_mul_f32_e32 v178, v146, v213
	v_mul_f32_e32 v178, v178, v50
	v_mul_f32_e32 v179, v147, v213
	v_mul_f32_e32 v179, v179, v51
	v_mul_f32_e32 v180, v148, v213
	v_mul_f32_e32 v180, v180, v52
	v_mul_f32_e32 v181, v149, v213
	v_mul_f32_e32 v181, v181, v53
	v_mul_f32_e32 v182, v150, v213
	v_mul_f32_e32 v182, v182, v54
	v_mul_f32_e32 v183, v151, v213
	v_mul_f32_e32 v183, v183, v55
	v_mul_f32_e32 v184, v152, v213
	v_mul_f32_e32 v184, v184, v56
	v_mul_f32_e32 v185, v153, v213
	v_mul_f32_e32 v185, v185, v57
	v_mul_f32_e32 v186, v154, v213
	v_mul_f32_e32 v186, v186, v58
	v_mul_f32_e32 v187, v155, v213
	v_mul_f32_e32 v187, v187, v59
	v_mul_f32_e32 v188, v156, v213
	v_mul_f32_e32 v188, v188, v60
	v_mul_f32_e32 v189, v157, v213
	v_mul_f32_e32 v189, v189, v61
	v_mul_f32_e32 v190, v158, v213
	v_mul_f32_e32 v190, v190, v62
	v_mul_f32_e32 v191, v159, v213
	v_mul_f32_e32 v191, v191, v63
	v_mul_f32_e32 v192, v160, v213
	v_mul_f32_e32 v192, v192, v64
	v_mul_f32_e32 v193, v161, v213
	v_mul_f32_e32 v193, v193, v65
	v_mul_f32_e32 v194, v162, v213
	v_mul_f32_e32 v194, v194, v66
	v_mul_f32_e32 v195, v163, v213
	v_mul_f32_e32 v195, v195, v67
	v_mul_f32_e32 v196, v164, v213
	v_mul_f32_e32 v196, v196, v68
	v_mul_f32_e32 v197, v165, v213
	v_mul_f32_e32 v197, v197, v69
	v_mul_f32_e32 v198, v166, v213
	v_mul_f32_e32 v198, v198, v70
	v_mul_f32_e32 v199, v167, v213
	v_mul_f32_e32 v199, v199, v71
	v_mul_f32_e32 v200, v168, v213
	v_mul_f32_e32 v200, v200, v72
	v_mul_f32_e32 v201, v169, v213
	v_mul_f32_e32 v201, v201, v73
	v_mul_f32_e32 v202, v170, v213
	v_mul_f32_e32 v202, v202, v74
	v_mul_f32_e32 v203, v171, v213
	v_mul_f32_e32 v203, v203, v75
	v_cvt_pk_bf16_f32 v124, v172, v173
	v_cvt_pk_bf16_f32 v125, v174, v175
	v_cvt_pk_bf16_f32 v126, v176, v177
	v_cvt_pk_bf16_f32 v127, v178, v179
	v_cvt_pk_bf16_f32 v128, v180, v181
	v_cvt_pk_bf16_f32 v129, v182, v183
	v_cvt_pk_bf16_f32 v130, v184, v185
	v_cvt_pk_bf16_f32 v131, v186, v187
	v_cvt_pk_bf16_f32 v132, v188, v189
	v_cvt_pk_bf16_f32 v133, v190, v191
	v_cvt_pk_bf16_f32 v134, v192, v193
	v_cvt_pk_bf16_f32 v135, v194, v195
	v_cvt_pk_bf16_f32 v136, v196, v197
	v_cvt_pk_bf16_f32 v137, v198, v199
	v_cvt_pk_bf16_f32 v138, v200, v201
	v_cvt_pk_bf16_f32 v139, v202, v203
	global_store_dwordx4 v0, v[124:127], s[16:17]
	global_store_dwordx4 v0, v[128:131], s[16:17] offset:1024
	global_store_dwordx4 v0, v[132:135], s[16:17] offset:2048
	global_store_dwordx4 v0, v[136:139], s[16:17] offset:3072
	s_mov_b32 s2, s29
	s_cmp_ge_u32 s2, 0x2080
	s_cbranch_scc0 .Lp6_A

.LBB0_1383:
	s_or_b64 exec, exec, s[2:3]
	v_mov_b32_e32 v8, v208
	s_waitcnt lgkmcnt(0)
	s_barrier
	s_add_u32 s10, s96, 0x1d300000
	s_addc_u32 s11, s97, 0
	s_add_u32 s12, s96, 0x1f300000
	s_addc_u32 s13, s97, 0
	s_and_b64 vcc, exec, s[0:1]
	v_readfirstlane_b32 s33, v8
	s_cbranch_vccnz .LBB0_1407
	s_lshr_b32 s2, s58, 29
	s_add_i32 s6, s47, s2
	s_and_b32 s2, s6, -8
	s_sub_i32 s5, s47, s2
	s_cmp_gt_i32 s5, -1
	s_cbranch_scc0 .LBB0_1386
	s_lshl_b32 s4, s5, 5
	s_ashr_i32 s6, s6, 3
	s_cbranch_execz .LBB0_1387
	s_branch .LBB0_1388

.LBB0_1462:
	s_or_b64 exec, exec, s[0:1]
	s_waitcnt lgkmcnt(0)
	s_barrier
	v_and_b32_e32 v3, 63, v208
	v_lshrrev_b32_e32 v4, 6, v208
	v_readlane_b32 s18, v252, 16
	v_readlane_b32 s19, v252, 17
	v_readlane_b32 s22, v252, 2
	v_readlane_b32 s23, v252, 3
	v_lshlrev_b32_e32 v0, 4, v3
	v_readfirstlane_b32 s2, v4
	v_lshlrev_b32_e32 v1, 5, v3
	v_lshlrev_b32_e32 v4, 2, v3
	v_add_u32_e32 v2, 0x1000, v1
	v_xor_b32_e32 v5, 0x80, v4
	v_xor_b32_e32 v6, 64, v4
	v_xor_b32_e32 v7, 32, v4
	v_xor_b32_e32 v8, 16, v4
	v_xor_b32_e32 v9, 8, v4
	v_xor_b32_e32 v10, 4, v4
	v_mov_b32_e32 v11, 0x358637bd
	s_add_i32 s2, s2, s74
	s_mov_b32 s3, s50
	s_add_u32 s20, s18, 0x2000
	s_addc_u32 s21, s19, 0
	s_add_u32 s24, s96, 0x20cc0000
	s_addc_u32 s25, s97, 0
	s_add_u32 s26, s96, 0x1d300000
	s_addc_u32 s27, s97, 0
	s_cmp_ge_u32 s2, 0x2080
	s_cbranch_scc1 .Lp10_done
	global_load_dwordx4 v[12:15], v1, s[18:19]
	global_load_dwordx4 v[16:19], v1, s[18:19] offset:16
	global_load_dwordx4 v[20:23], v1, s[18:19] offset:2048
	global_load_dwordx4 v[24:27], v1, s[18:19] offset:2064
	global_load_dwordx4 v[28:31], v2, s[18:19]
	global_load_dwordx4 v[32:35], v2, s[18:19] offset:16
	global_load_dwordx4 v[36:39], v2, s[18:19] offset:2048
	global_load_dwordx4 v[40:43], v2, s[18:19] offset:2064
	global_load_dwordx4 v[44:47], v1, s[20:21]
	global_load_dwordx4 v[48:51], v1, s[20:21] offset:16
	global_load_dwordx4 v[52:55], v1, s[20:21] offset:2048
	global_load_dwordx4 v[56:59], v1, s[20:21] offset:2064
	global_load_dwordx4 v[60:63], v2, s[20:21]
	global_load_dwordx4 v[64:67], v2, s[20:21] offset:16
	global_load_dwordx4 v[68:71], v2, s[20:21] offset:2048
	global_load_dwordx4 v[72:75], v2, s[20:21] offset:2064
	s_lshl_b32 s4, s2, 12
	s_add_u32 s6, s24, s4
	s_addc_u32 s7, s25, 0
	s_add_u32 s16, s26, s4
	s_addc_u32 s17, s27, 0
	s_lshl_b32 s4, s2, 13
	s_cmp_lt_u32 s2, 0x2000
	s_cselect_b32 s8, s98, s100
	s_cselect_b32 s9, s99, s101
	s_cselect_b32 s28, 0, 0x4000000
	s_sub_u32 s4, s4, s28
	s_add_u32 s8, s8, s4
	s_addc_u32 s9, s9, 0
	global_load_dwordx4 v[76:79], v0, s[6:7]
	global_load_dwordx4 v[80:83], v0, s[6:7] offset:1024
	global_load_dwordx4 v[84:87], v0, s[6:7] offset:2048
	global_load_dwordx4 v[88:91], v0, s[6:7] offset:3072
	global_load_dwordx4 v[92:95], v0, s[16:17]
	global_load_dwordx4 v[96:99], v0, s[16:17] offset:1024
	global_load_dwordx4 v[100:103], v0, s[16:17] offset:2048
	global_load_dwordx4 v[104:107], v0, s[16:17] offset:3072
	global_load_dwordx4 v[108:111], v1, s[8:9]
	global_load_dwordx4 v[112:115], v1, s[8:9] offset:16
	global_load_dwordx4 v[116:119], v1, s[8:9] offset:2048
	global_load_dwordx4 v[120:123], v1, s[8:9] offset:2064
	global_load_dwordx4 v[124:127], v2, s[8:9]
	global_load_dwordx4 v[128:131], v2, s[8:9] offset:16
	global_load_dwordx4 v[132:135], v2, s[8:9] offset:2048
	global_load_dwordx4 v[136:139], v2, s[8:9] offset:2064
	s_waitcnt vmcnt(0)
	s_branch .Lp10_A_go

.Lp10_A_go:
	s_add_u32 s29, s2, s3
	s_cmp_ge_u32 s29, 0x2080
	s_cbranch_scc1 .Lp10_A_nopf
	s_lshl_b32 s4, s29, 12
	s_add_u32 s6, s24, s4
	s_addc_u32 s7, s25, 0
	s_add_u32 s16, s26, s4
	s_addc_u32 s17, s27, 0
	s_lshl_b32 s4, s29, 13
	s_cmp_lt_u32 s29, 0x2000
	s_cselect_b32 s8, s98, s100
	s_cselect_b32 s9, s99, s101
	s_cselect_b32 s28, 0, 0x4000000
	s_sub_u32 s4, s4, s28
	s_add_u32 s8, s8, s4
	s_addc_u32 s9, s9, 0
	global_load_dwordx4 v[140:143], v0, s[6:7]
	global_load_dwordx4 v[144:147], v0, s[6:7] offset:1024
	global_load_dwordx4 v[148:151], v0, s[6:7] offset:2048
	global_load_dwordx4 v[152:155], v0, s[6:7] offset:3072
	global_load_dwordx4 v[156:159], v0, s[16:17]
	global_load_dwordx4 v[160:163], v0, s[16:17] offset:1024
	global_load_dwordx4 v[164:167], v0, s[16:17] offset:2048
	global_load_dwordx4 v[168:171], v0, s[16:17] offset:3072
	global_load_dwordx4 v[172:175], v1, s[8:9]
	global_load_dwordx4 v[176:179], v1, s[8:9] offset:16
	global_load_dwordx4 v[180:183], v1, s[8:9] offset:2048
	global_load_dwordx4 v[184:187], v1, s[8:9] offset:2064
	global_load_dwordx4 v[188:191], v2, s[8:9]
	global_load_dwordx4 v[192:195], v2, s[8:9] offset:16
	global_load_dwordx4 v[196:199], v2, s[8:9] offset:2048
	global_load_dwordx4 v[200:203], v2, s[8:9] offset:2064
.Lp10_A_nopf:
	v_lshlrev_b32_e32 v204, 16, v76
	v_and_b32_e32 v205, 0xffff0000, v76
	v_lshlrev_b32_e32 v206, 16, v77
	v_and_b32_e32 v207, 0xffff0000, v77
	v_lshlrev_b32_e32 v210, 16, v78
	v_and_b32_e32 v211, 0xffff0000, v78
	v_lshlrev_b32_e32 v212, 16, v79
	v_and_b32_e32 v213, 0xffff0000, v79
	v_lshlrev_b32_e32 v214, 16, v80
	v_and_b32_e32 v215, 0xffff0000, v80
	v_lshlrev_b32_e32 v216, 16, v81
	v_and_b32_e32 v217, 0xffff0000, v81
	v_lshlrev_b32_e32 v218, 16, v82
	v_and_b32_e32 v219, 0xffff0000, v82
	v_lshlrev_b32_e32 v220, 16, v83
	v_and_b32_e32 v221, 0xffff0000, v83
	v_lshlrev_b32_e32 v222, 16, v84
	v_and_b32_e32 v223, 0xffff0000, v84
	v_lshlrev_b32_e32 v224, 16, v85
	v_and_b32_e32 v225, 0xffff0000, v85
	v_lshlrev_b32_e32 v226, 16, v86
	v_and_b32_e32 v227, 0xffff0000, v86
	v_lshlrev_b32_e32 v228, 16, v87
	v_and_b32_e32 v229, 0xffff0000, v87
	v_lshlrev_b32_e32 v230, 16, v88
	v_and_b32_e32 v231, 0xffff0000, v88
	v_lshlrev_b32_e32 v232, 16, v89
	v_and_b32_e32 v233, 0xffff0000, v89
	v_lshlrev_b32_e32 v234, 16, v90
	v_and_b32_e32 v235, 0xffff0000, v90
	v_lshlrev_b32_e32 v236, 16, v91
	v_and_b32_e32 v237, 0xffff0000, v91
	v_mul_f32_e32 v238, v204, v204
	v_mul_f32_e32 v239, v205, v205
	v_mul_f32_e32 v240, v206, v206
	v_mul_f32_e32 v241, v207, v207
	v_fmac_f32_e32 v238, v210, v210
	v_fmac_f32_e32 v239, v211, v211
	v_fmac_f32_e32 v240, v212, v212
	v_fmac_f32_e32 v241, v213, v213
	v_fmac_f32_e32 v238, v214, v214
	v_fmac_f32_e32 v239, v215, v215
	v_fmac_f32_e32 v240, v216, v216
	v_fmac_f32_e32 v241, v217, v217
	v_fmac_f32_e32 v238, v218, v218
	v_fmac_f32_e32 v239, v219, v219
	v_fmac_f32_e32 v240, v220, v220
	v_fmac_f32_e32 v241, v221, v221
	v_fmac_f32_e32 v238, v222, v222
	v_fmac_f32_e32 v239, v223, v223
	v_fmac_f32_e32 v240, v224, v224
	v_fmac_f32_e32 v241, v225, v225
	v_fmac_f32_e32 v238, v226, v226
	v_fmac_f32_e32 v239, v227, v227
	v_fmac_f32_e32 v240, v228, v228
	v_fmac_f32_e32 v241, v229, v229
	v_fmac_f32_e32 v238, v230, v230
	v_fmac_f32_e32 v239, v231, v231
	v_fmac_f32_e32 v240, v232, v232
	v_fmac_f32_e32 v241, v233, v233
	v_fmac_f32_e32 v238, v234, v234
	v_fmac_f32_e32 v239, v235, v235
	v_fmac_f32_e32 v240, v236, v236
	v_fmac_f32_e32 v241, v237, v237
	v_add_f32_e32 v238, v238, v239
	v_add_f32_e32 v240, v240, v241
	v_add_f32_e32 v238, v238, v240
	ds_bpermute_b32 v242, v5, v238
	s_waitcnt lgkmcnt(0)
	v_add_f32_e32 v238, v238, v242
	ds_bpermute_b32 v242, v6, v238
	s_waitcnt lgkmcnt(0)
	v_add_f32_e32 v238, v238, v242
	ds_bpermute_b32 v242, v7, v238
	s_waitcnt lgkmcnt(0)
	v_add_f32_e32 v238, v238, v242
	ds_bpermute_b32 v242, v8, v238
	s_waitcnt lgkmcnt(0)
	v_add_f32_e32 v238, v238, v242
	ds_bpermute_b32 v242, v9, v238
	s_waitcnt lgkmcnt(0)
	v_add_f32_e32 v238, v238, v242
	ds_bpermute_b32 v242, v10, v238
	s_waitcnt lgkmcnt(0)
	v_add_f32_e32 v238, v238, v242
	v_fmamk_f32 v238, v238, 0x3a000000, v11
	v_rsq_f32_e32 v243, v238
	s_nop 0
	v_mul_f32_e32 v204, v204, v243
	v_fmac_f32_e32 v108, v204, v12
	v_mul_f32_e32 v205, v205, v243
	v_fmac_f32_e32 v109, v205, v13
	v_mul_f32_e32 v206, v206, v243
	v_fmac_f32_e32 v110, v206, v14
	v_mul_f32_e32 v207, v207, v243
	v_fmac_f32_e32 v111, v207, v15
	v_mul_f32_e32 v210, v210, v243
	v_fmac_f32_e32 v112, v210, v16
	v_mul_f32_e32 v211, v211, v243
	v_fmac_f32_e32 v113, v211, v17
	v_mul_f32_e32 v212, v212, v243
	v_fmac_f32_e32 v114, v212, v18
	v_mul_f32_e32 v213, v213, v243
	v_fmac_f32_e32 v115, v213, v19
	v_mul_f32_e32 v214, v214, v243
	v_fmac_f32_e32 v116, v214, v20
	v_mul_f32_e32 v215, v215, v243
	v_fmac_f32_e32 v117, v215, v21
	v_mul_f32_e32 v216, v216, v243
	v_fmac_f32_e32 v118, v216, v22
	v_mul_f32_e32 v217, v217, v243
	v_fmac_f32_e32 v119, v217, v23
	v_mul_f32_e32 v218, v218, v243
	v_fmac_f32_e32 v120, v218, v24
	v_mul_f32_e32 v219, v219, v243
	v_fmac_f32_e32 v121, v219, v25
	v_mul_f32_e32 v220, v220, v243
	v_fmac_f32_e32 v122, v220, v26
	v_mul_f32_e32 v221, v221, v243
	v_fmac_f32_e32 v123, v221, v27
	v_mul_f32_e32 v222, v222, v243
	v_fmac_f32_e32 v124, v222, v28
	v_mul_f32_e32 v223, v223, v243
	v_fmac_f32_e32 v125, v223, v29
	v_mul_f32_e32 v224, v224, v243
	v_fmac_f32_e32 v126, v224, v30
	v_mul_f32_e32 v225, v225, v243
	v_fmac_f32_e32 v127, v225, v31
	v_mul_f32_e32 v226, v226, v243
	v_fmac_f32_e32 v128, v226, v32
	v_mul_f32_e32 v227, v227, v243
	v_fmac_f32_e32 v129, v227, v33
	v_mul_f32_e32 v228, v228, v243
	v_fmac_f32_e32 v130, v228, v34
	v_mul_f32_e32 v229, v229, v243
	v_fmac_f32_e32 v131, v229, v35
	v_mul_f32_e32 v230, v230, v243
	v_fmac_f32_e32 v132, v230, v36
	v_mul_f32_e32 v231, v231, v243
	v_fmac_f32_e32 v133, v231, v37
	v_mul_f32_e32 v232, v232, v243
	v_fmac_f32_e32 v134, v232, v38
	v_mul_f32_e32 v233, v233, v243
	v_fmac_f32_e32 v135, v233, v39
	v_mul_f32_e32 v234, v234, v243
	v_fmac_f32_e32 v136, v234, v40
	v_mul_f32_e32 v235, v235, v243
	v_fmac_f32_e32 v137, v235, v41
	v_mul_f32_e32 v236, v236, v243
	v_fmac_f32_e32 v138, v236, v42
	v_mul_f32_e32 v237, v237, v243
	v_fmac_f32_e32 v139, v237, v43
	v_lshlrev_b32_e32 v204, 16, v92
	v_and_b32_e32 v205, 0xffff0000, v92
	v_lshlrev_b32_e32 v206, 16, v93
	v_and_b32_e32 v207, 0xffff0000, v93
	v_lshlrev_b32_e32 v210, 16, v94
	v_and_b32_e32 v211, 0xffff0000, v94
	v_lshlrev_b32_e32 v212, 16, v95
	v_and_b32_e32 v213, 0xffff0000, v95
	v_lshlrev_b32_e32 v214, 16, v96
	v_and_b32_e32 v215, 0xffff0000, v96
	v_lshlrev_b32_e32 v216, 16, v97
	v_and_b32_e32 v217, 0xffff0000, v97
	v_lshlrev_b32_e32 v218, 16, v98
	v_and_b32_e32 v219, 0xffff0000, v98
	v_lshlrev_b32_e32 v220, 16, v99
	v_and_b32_e32 v221, 0xffff0000, v99
	v_lshlrev_b32_e32 v222, 16, v100
	v_and_b32_e32 v223, 0xffff0000, v100
	v_lshlrev_b32_e32 v224, 16, v101
	v_and_b32_e32 v225, 0xffff0000, v101
	v_lshlrev_b32_e32 v226, 16, v102
	v_and_b32_e32 v227, 0xffff0000, v102
	v_lshlrev_b32_e32 v228, 16, v103
	v_and_b32_e32 v229, 0xffff0000, v103
	v_lshlrev_b32_e32 v230, 16, v104
	v_and_b32_e32 v231, 0xffff0000, v104
	v_lshlrev_b32_e32 v232, 16, v105
	v_and_b32_e32 v233, 0xffff0000, v105
	v_lshlrev_b32_e32 v234, 16, v106
	v_and_b32_e32 v235, 0xffff0000, v106
	v_lshlrev_b32_e32 v236, 16, v107
	v_and_b32_e32 v237, 0xffff0000, v107
	v_mul_f32_e32 v238, v204, v204
	v_mul_f32_e32 v239, v205, v205
	v_mul_f32_e32 v240, v206, v206
	v_mul_f32_e32 v241, v207, v207
	v_fmac_f32_e32 v238, v210, v210
	v_fmac_f32_e32 v239, v211, v211
	v_fmac_f32_e32 v240, v212, v212
	v_fmac_f32_e32 v241, v213, v213
	v_fmac_f32_e32 v238, v214, v214
	v_fmac_f32_e32 v239, v215, v215
	v_fmac_f32_e32 v240, v216, v216
	v_fmac_f32_e32 v241, v217, v217
	v_fmac_f32_e32 v238, v218, v218
	v_fmac_f32_e32 v239, v219, v219
	v_fmac_f32_e32 v240, v220, v220
	v_fmac_f32_e32 v241, v221, v221
	v_fmac_f32_e32 v238, v222, v222
	v_fmac_f32_e32 v239, v223, v223
	v_fmac_f32_e32 v240, v224, v224
	v_fmac_f32_e32 v241, v225, v225
	v_fmac_f32_e32 v238, v226, v226
	v_fmac_f32_e32 v239, v227, v227
	v_fmac_f32_e32 v240, v228, v228
	v_fmac_f32_e32 v241, v229, v229
	v_fmac_f32_e32 v238, v230, v230
	v_fmac_f32_e32 v239, v231, v231
	v_fmac_f32_e32 v240, v232, v232
	v_fmac_f32_e32 v241, v233, v233
	v_fmac_f32_e32 v238, v234, v234
	v_fmac_f32_e32 v239, v235, v235
	v_fmac_f32_e32 v240, v236, v236
	v_fmac_f32_e32 v241, v237, v237
	v_add_f32_e32 v238, v238, v239
	v_add_f32_e32 v240, v240, v241
	v_add_f32_e32 v238, v238, v240
	ds_bpermute_b32 v242, v5, v238
	s_waitcnt lgkmcnt(0)
	v_add_f32_e32 v238, v238, v242
	ds_bpermute_b32 v242, v6, v238
	s_waitcnt lgkmcnt(0)
	v_add_f32_e32 v238, v238, v242
	ds_bpermute_b32 v242, v7, v238
	s_waitcnt lgkmcnt(0)
	v_add_f32_e32 v238, v238, v242
	ds_bpermute_b32 v242, v8, v238
	s_waitcnt lgkmcnt(0)
	v_add_f32_e32 v238, v238, v242
	ds_bpermute_b32 v242, v9, v238
	s_waitcnt lgkmcnt(0)
	v_add_f32_e32 v238, v238, v242
	ds_bpermute_b32 v242, v10, v238
	s_waitcnt lgkmcnt(0)
	v_add_f32_e32 v238, v238, v242
	v_fmamk_f32 v238, v238, 0x3a000000, v11
	v_rsq_f32_e32 v243, v238
	s_nop 0
	v_mul_f32_e32 v204, v204, v243
	v_fmac_f32_e32 v108, v204, v44
	v_mul_f32_e32 v205, v205, v243
	v_fmac_f32_e32 v109, v205, v45
	v_mul_f32_e32 v206, v206, v243
	v_fmac_f32_e32 v110, v206, v46
	v_mul_f32_e32 v207, v207, v243
	v_fmac_f32_e32 v111, v207, v47
	v_mul_f32_e32 v210, v210, v243
	v_fmac_f32_e32 v112, v210, v48
	v_mul_f32_e32 v211, v211, v243
	v_fmac_f32_e32 v113, v211, v49
	v_mul_f32_e32 v212, v212, v243
	v_fmac_f32_e32 v114, v212, v50
	v_mul_f32_e32 v213, v213, v243
	v_fmac_f32_e32 v115, v213, v51
	v_mul_f32_e32 v214, v214, v243
	v_fmac_f32_e32 v116, v214, v52
	v_mul_f32_e32 v215, v215, v243
	v_fmac_f32_e32 v117, v215, v53
	v_mul_f32_e32 v216, v216, v243
	v_fmac_f32_e32 v118, v216, v54
	v_mul_f32_e32 v217, v217, v243
	v_fmac_f32_e32 v119, v217, v55
	v_mul_f32_e32 v218, v218, v243
	v_fmac_f32_e32 v120, v218, v56
	v_mul_f32_e32 v219, v219, v243
	v_fmac_f32_e32 v121, v219, v57
	v_mul_f32_e32 v220, v220, v243
	v_fmac_f32_e32 v122, v220, v58
	v_mul_f32_e32 v221, v221, v243
	v_fmac_f32_e32 v123, v221, v59
	v_mul_f32_e32 v222, v222, v243
	v_fmac_f32_e32 v124, v222, v60
	v_mul_f32_e32 v223, v223, v243
	v_fmac_f32_e32 v125, v223, v61
	v_mul_f32_e32 v224, v224, v243
	v_fmac_f32_e32 v126, v224, v62
	v_mul_f32_e32 v225, v225, v243
	v_fmac_f32_e32 v127, v225, v63
	v_mul_f32_e32 v226, v226, v243
	v_fmac_f32_e32 v128, v226, v64
	v_mul_f32_e32 v227, v227, v243
	v_fmac_f32_e32 v129, v227, v65
	v_mul_f32_e32 v228, v228, v243
	v_fmac_f32_e32 v130, v228, v66
	v_mul_f32_e32 v229, v229, v243
	v_fmac_f32_e32 v131, v229, v67
	v_mul_f32_e32 v230, v230, v243
	v_fmac_f32_e32 v132, v230, v68
	v_mul_f32_e32 v231, v231, v243
	v_fmac_f32_e32 v133, v231, v69
	v_mul_f32_e32 v232, v232, v243
	v_fmac_f32_e32 v134, v232, v70
	v_mul_f32_e32 v233, v233, v243
	v_fmac_f32_e32 v135, v233, v71
	v_mul_f32_e32 v234, v234, v243
	v_fmac_f32_e32 v136, v234, v72
	v_mul_f32_e32 v235, v235, v243
	v_fmac_f32_e32 v137, v235, v73
	v_mul_f32_e32 v236, v236, v243
	v_fmac_f32_e32 v138, v236, v74
	v_mul_f32_e32 v237, v237, v243
	v_fmac_f32_e32 v139, v237, v75
	s_lshl_b32 s4, s2, 13
	s_add_u32 s14, s22, s4
	s_addc_u32 s15, s23, 0
	global_store_dwordx4 v1, v[108:111], s[14:15]
	global_store_dwordx4 v1, v[112:115], s[14:15] offset:16
	global_store_dwordx4 v1, v[116:119], s[14:15] offset:2048
	global_store_dwordx4 v1, v[120:123], s[14:15] offset:2064
	global_store_dwordx4 v2, v[124:127], s[14:15]
	global_store_dwordx4 v2, v[128:131], s[14:15] offset:16
	global_store_dwordx4 v2, v[132:135], s[14:15] offset:2048
	global_store_dwordx4 v2, v[136:139], s[14:15] offset:2064
	s_mov_b32 s2, s29
	s_cmp_ge_u32 s2, 0x2080
	s_cbranch_scc1 .Lp10_done
.Lp10_B:
	s_waitcnt vmcnt(8)
	s_add_u32 s29, s2, s3
	s_cmp_ge_u32 s29, 0x2080
	s_cbranch_scc1 .Lp10_B_nopf
	s_lshl_b32 s4, s29, 12
	s_add_u32 s6, s24, s4
	s_addc_u32 s7, s25, 0
	s_add_u32 s16, s26, s4
	s_addc_u32 s17, s27, 0
	s_lshl_b32 s4, s29, 13
	s_cmp_lt_u32 s29, 0x2000
	s_cselect_b32 s8, s98, s100
	s_cselect_b32 s9, s99, s101
	s_cselect_b32 s28, 0, 0x4000000
	s_sub_u32 s4, s4, s28
	s_add_u32 s8, s8, s4
	s_addc_u32 s9, s9, 0
	global_load_dwordx4 v[76:79], v0, s[6:7]
	global_load_dwordx4 v[80:83], v0, s[6:7] offset:1024
	global_load_dwordx4 v[84:87], v0, s[6:7] offset:2048
	global_load_dwordx4 v[88:91], v0, s[6:7] offset:3072
	global_load_dwordx4 v[92:95], v0, s[16:17]
	global_load_dwordx4 v[96:99], v0, s[16:17] offset:1024
	global_load_dwordx4 v[100:103], v0, s[16:17] offset:2048
	global_load_dwordx4 v[104:107], v0, s[16:17] offset:3072
	global_load_dwordx4 v[108:111], v1, s[8:9]
	global_load_dwordx4 v[112:115], v1, s[8:9] offset:16
	global_load_dwordx4 v[116:119], v1, s[8:9] offset:2048
	global_load_dwordx4 v[120:123], v1, s[8:9] offset:2064
	global_load_dwordx4 v[124:127], v2, s[8:9]
	global_load_dwordx4 v[128:131], v2, s[8:9] offset:16
	global_load_dwordx4 v[132:135], v2, s[8:9] offset:2048
	global_load_dwordx4 v[136:139], v2, s[8:9] offset:2064
.Lp10_B_nopf:
	v_lshlrev_b32_e32 v204, 16, v140
	v_and_b32_e32 v205, 0xffff0000, v140
	v_lshlrev_b32_e32 v206, 16, v141
	v_and_b32_e32 v207, 0xffff0000, v141
	v_lshlrev_b32_e32 v210, 16, v142
	v_and_b32_e32 v211, 0xffff0000, v142
	v_lshlrev_b32_e32 v212, 16, v143
	v_and_b32_e32 v213, 0xffff0000, v143
	v_lshlrev_b32_e32 v214, 16, v144
	v_and_b32_e32 v215, 0xffff0000, v144
	v_lshlrev_b32_e32 v216, 16, v145
	v_and_b32_e32 v217, 0xffff0000, v145
	v_lshlrev_b32_e32 v218, 16, v146
	v_and_b32_e32 v219, 0xffff0000, v146
	v_lshlrev_b32_e32 v220, 16, v147
	v_and_b32_e32 v221, 0xffff0000, v147
	v_lshlrev_b32_e32 v222, 16, v148
	v_and_b32_e32 v223, 0xffff0000, v148
	v_lshlrev_b32_e32 v224, 16, v149
	v_and_b32_e32 v225, 0xffff0000, v149
	v_lshlrev_b32_e32 v226, 16, v150
	v_and_b32_e32 v227, 0xffff0000, v150
	v_lshlrev_b32_e32 v228, 16, v151
	v_and_b32_e32 v229, 0xffff0000, v151
	v_lshlrev_b32_e32 v230, 16, v152
	v_and_b32_e32 v231, 0xffff0000, v152
	v_lshlrev_b32_e32 v232, 16, v153
	v_and_b32_e32 v233, 0xffff0000, v153
	v_lshlrev_b32_e32 v234, 16, v154
	v_and_b32_e32 v235, 0xffff0000, v154
	v_lshlrev_b32_e32 v236, 16, v155
	v_and_b32_e32 v237, 0xffff0000, v155
	v_mul_f32_e32 v238, v204, v204
	v_mul_f32_e32 v239, v205, v205
	v_mul_f32_e32 v240, v206, v206
	v_mul_f32_e32 v241, v207, v207
	v_fmac_f32_e32 v238, v210, v210
	v_fmac_f32_e32 v239, v211, v211
	v_fmac_f32_e32 v240, v212, v212
	v_fmac_f32_e32 v241, v213, v213
	v_fmac_f32_e32 v238, v214, v214
	v_fmac_f32_e32 v239, v215, v215
	v_fmac_f32_e32 v240, v216, v216
	v_fmac_f32_e32 v241, v217, v217
	v_fmac_f32_e32 v238, v218, v218
	v_fmac_f32_e32 v239, v219, v219
	v_fmac_f32_e32 v240, v220, v220
	v_fmac_f32_e32 v241, v221, v221
	v_fmac_f32_e32 v238, v222, v222
	v_fmac_f32_e32 v239, v223, v223
	v_fmac_f32_e32 v240, v224, v224
	v_fmac_f32_e32 v241, v225, v225
	v_fmac_f32_e32 v238, v226, v226
	v_fmac_f32_e32 v239, v227, v227
	v_fmac_f32_e32 v240, v228, v228
	v_fmac_f32_e32 v241, v229, v229
	v_fmac_f32_e32 v238, v230, v230
	v_fmac_f32_e32 v239, v231, v231
	v_fmac_f32_e32 v240, v232, v232
	v_fmac_f32_e32 v241, v233, v233
	v_fmac_f32_e32 v238, v234, v234
	v_fmac_f32_e32 v239, v235, v235
	v_fmac_f32_e32 v240, v236, v236
	v_fmac_f32_e32 v241, v237, v237
	v_add_f32_e32 v238, v238, v239
	v_add_f32_e32 v240, v240, v241
	v_add_f32_e32 v238, v238, v240
	ds_bpermute_b32 v242, v5, v238
	s_waitcnt lgkmcnt(0)
	v_add_f32_e32 v238, v238, v242
	ds_bpermute_b32 v242, v6, v238
	s_waitcnt lgkmcnt(0)
	v_add_f32_e32 v238, v238, v242
	ds_bpermute_b32 v242, v7, v238
	s_waitcnt lgkmcnt(0)
	v_add_f32_e32 v238, v238, v242
	ds_bpermute_b32 v242, v8, v238
	s_waitcnt lgkmcnt(0)
	v_add_f32_e32 v238, v238, v242
	ds_bpermute_b32 v242, v9, v238
	s_waitcnt lgkmcnt(0)
	v_add_f32_e32 v238, v238, v242
	ds_bpermute_b32 v242, v10, v238
	s_waitcnt lgkmcnt(0)
	v_add_f32_e32 v238, v238, v242
	v_fmamk_f32 v238, v238, 0x3a000000, v11
	v_rsq_f32_e32 v243, v238
	s_nop 0
	v_mul_f32_e32 v204, v204, v243
	v_fmac_f32_e32 v172, v204, v12
	v_mul_f32_e32 v205, v205, v243
	v_fmac_f32_e32 v173, v205, v13
	v_mul_f32_e32 v206, v206, v243
	v_fmac_f32_e32 v174, v206, v14
	v_mul_f32_e32 v207, v207, v243
	v_fmac_f32_e32 v175, v207, v15
	v_mul_f32_e32 v210, v210, v243
	v_fmac_f32_e32 v176, v210, v16
	v_mul_f32_e32 v211, v211, v243
	v_fmac_f32_e32 v177, v211, v17
	v_mul_f32_e32 v212, v212, v243
	v_fmac_f32_e32 v178, v212, v18
	v_mul_f32_e32 v213, v213, v243
	v_fmac_f32_e32 v179, v213, v19
	v_mul_f32_e32 v214, v214, v243
	v_fmac_f32_e32 v180, v214, v20
	v_mul_f32_e32 v215, v215, v243
	v_fmac_f32_e32 v181, v215, v21
	v_mul_f32_e32 v216, v216, v243
	v_fmac_f32_e32 v182, v216, v22
	v_mul_f32_e32 v217, v217, v243
	v_fmac_f32_e32 v183, v217, v23
	v_mul_f32_e32 v218, v218, v243
	v_fmac_f32_e32 v184, v218, v24
	v_mul_f32_e32 v219, v219, v243
	v_fmac_f32_e32 v185, v219, v25
	v_mul_f32_e32 v220, v220, v243
	v_fmac_f32_e32 v186, v220, v26
	v_mul_f32_e32 v221, v221, v243
	v_fmac_f32_e32 v187, v221, v27
	v_mul_f32_e32 v222, v222, v243
	v_fmac_f32_e32 v188, v222, v28
	v_mul_f32_e32 v223, v223, v243
	v_fmac_f32_e32 v189, v223, v29
	v_mul_f32_e32 v224, v224, v243
	v_fmac_f32_e32 v190, v224, v30
	v_mul_f32_e32 v225, v225, v243
	v_fmac_f32_e32 v191, v225, v31
	v_mul_f32_e32 v226, v226, v243
	v_fmac_f32_e32 v192, v226, v32
	v_mul_f32_e32 v227, v227, v243
	v_fmac_f32_e32 v193, v227, v33
	v_mul_f32_e32 v228, v228, v243
	v_fmac_f32_e32 v194, v228, v34
	v_mul_f32_e32 v229, v229, v243
	v_fmac_f32_e32 v195, v229, v35
	v_mul_f32_e32 v230, v230, v243
	v_fmac_f32_e32 v196, v230, v36
	v_mul_f32_e32 v231, v231, v243
	v_fmac_f32_e32 v197, v231, v37
	v_mul_f32_e32 v232, v232, v243
	v_fmac_f32_e32 v198, v232, v38
	v_mul_f32_e32 v233, v233, v243
	v_fmac_f32_e32 v199, v233, v39
	v_mul_f32_e32 v234, v234, v243
	v_fmac_f32_e32 v200, v234, v40
	v_mul_f32_e32 v235, v235, v243
	v_fmac_f32_e32 v201, v235, v41
	v_mul_f32_e32 v236, v236, v243
	v_fmac_f32_e32 v202, v236, v42
	v_mul_f32_e32 v237, v237, v243
	v_fmac_f32_e32 v203, v237, v43
	v_lshlrev_b32_e32 v204, 16, v156
	v_and_b32_e32 v205, 0xffff0000, v156
	v_lshlrev_b32_e32 v206, 16, v157
	v_and_b32_e32 v207, 0xffff0000, v157
	v_lshlrev_b32_e32 v210, 16, v158
	v_and_b32_e32 v211, 0xffff0000, v158
	v_lshlrev_b32_e32 v212, 16, v159
	v_and_b32_e32 v213, 0xffff0000, v159
	v_lshlrev_b32_e32 v214, 16, v160
	v_and_b32_e32 v215, 0xffff0000, v160
	v_lshlrev_b32_e32 v216, 16, v161
	v_and_b32_e32 v217, 0xffff0000, v161
	v_lshlrev_b32_e32 v218, 16, v162
	v_and_b32_e32 v219, 0xffff0000, v162
	v_lshlrev_b32_e32 v220, 16, v163
	v_and_b32_e32 v221, 0xffff0000, v163
	v_lshlrev_b32_e32 v222, 16, v164
	v_and_b32_e32 v223, 0xffff0000, v164
	v_lshlrev_b32_e32 v224, 16, v165
	v_and_b32_e32 v225, 0xffff0000, v165
	v_lshlrev_b32_e32 v226, 16, v166
	v_and_b32_e32 v227, 0xffff0000, v166
	v_lshlrev_b32_e32 v228, 16, v167
	v_and_b32_e32 v229, 0xffff0000, v167
	v_lshlrev_b32_e32 v230, 16, v168
	v_and_b32_e32 v231, 0xffff0000, v168
	v_lshlrev_b32_e32 v232, 16, v169
	v_and_b32_e32 v233, 0xffff0000, v169
	v_lshlrev_b32_e32 v234, 16, v170
	v_and_b32_e32 v235, 0xffff0000, v170
	v_lshlrev_b32_e32 v236, 16, v171
	v_and_b32_e32 v237, 0xffff0000, v171
	v_mul_f32_e32 v238, v204, v204
	v_mul_f32_e32 v239, v205, v205
	v_mul_f32_e32 v240, v206, v206
	v_mul_f32_e32 v241, v207, v207
	v_fmac_f32_e32 v238, v210, v210
	v_fmac_f32_e32 v239, v211, v211
	v_fmac_f32_e32 v240, v212, v212
	v_fmac_f32_e32 v241, v213, v213
	v_fmac_f32_e32 v238, v214, v214
	v_fmac_f32_e32 v239, v215, v215
	v_fmac_f32_e32 v240, v216, v216
	v_fmac_f32_e32 v241, v217, v217
	v_fmac_f32_e32 v238, v218, v218
	v_fmac_f32_e32 v239, v219, v219
	v_fmac_f32_e32 v240, v220, v220
	v_fmac_f32_e32 v241, v221, v221
	v_fmac_f32_e32 v238, v222, v222
	v_fmac_f32_e32 v239, v223, v223
	v_fmac_f32_e32 v240, v224, v224
	v_fmac_f32_e32 v241, v225, v225
	v_fmac_f32_e32 v238, v226, v226
	v_fmac_f32_e32 v239, v227, v227
	v_fmac_f32_e32 v240, v228, v228
	v_fmac_f32_e32 v241, v229, v229
	v_fmac_f32_e32 v238, v230, v230
	v_fmac_f32_e32 v239, v231, v231
	v_fmac_f32_e32 v240, v232, v232
	v_fmac_f32_e32 v241, v233, v233
	v_fmac_f32_e32 v238, v234, v234
	v_fmac_f32_e32 v239, v235, v235
	v_fmac_f32_e32 v240, v236, v236
	v_fmac_f32_e32 v241, v237, v237
	v_add_f32_e32 v238, v238, v239
	v_add_f32_e32 v240, v240, v241
	v_add_f32_e32 v238, v238, v240
	ds_bpermute_b32 v242, v5, v238
	s_waitcnt lgkmcnt(0)
	v_add_f32_e32 v238, v238, v242
	ds_bpermute_b32 v242, v6, v238
	s_waitcnt lgkmcnt(0)
	v_add_f32_e32 v238, v238, v242
	ds_bpermute_b32 v242, v7, v238
	s_waitcnt lgkmcnt(0)
	v_add_f32_e32 v238, v238, v242
	ds_bpermute_b32 v242, v8, v238
	s_waitcnt lgkmcnt(0)
	v_add_f32_e32 v238, v238, v242
	ds_bpermute_b32 v242, v9, v238
	s_waitcnt lgkmcnt(0)
	v_add_f32_e32 v238, v238, v242
	ds_bpermute_b32 v242, v10, v238
	s_waitcnt lgkmcnt(0)
	v_add_f32_e32 v238, v238, v242
	v_fmamk_f32 v238, v238, 0x3a000000, v11
	v_rsq_f32_e32 v243, v238
	s_nop 0
	v_mul_f32_e32 v204, v204, v243
	v_fmac_f32_e32 v172, v204, v44
	v_mul_f32_e32 v205, v205, v243
	v_fmac_f32_e32 v173, v205, v45
	v_mul_f32_e32 v206, v206, v243
	v_fmac_f32_e32 v174, v206, v46
	v_mul_f32_e32 v207, v207, v243
	v_fmac_f32_e32 v175, v207, v47
	v_mul_f32_e32 v210, v210, v243
	v_fmac_f32_e32 v176, v210, v48
	v_mul_f32_e32 v211, v211, v243
	v_fmac_f32_e32 v177, v211, v49
	v_mul_f32_e32 v212, v212, v243
	v_fmac_f32_e32 v178, v212, v50
	v_mul_f32_e32 v213, v213, v243
	v_fmac_f32_e32 v179, v213, v51
	v_mul_f32_e32 v214, v214, v243
	v_fmac_f32_e32 v180, v214, v52
	v_mul_f32_e32 v215, v215, v243
	v_fmac_f32_e32 v181, v215, v53
	v_mul_f32_e32 v216, v216, v243
	v_fmac_f32_e32 v182, v216, v54
	v_mul_f32_e32 v217, v217, v243
	v_fmac_f32_e32 v183, v217, v55
	v_mul_f32_e32 v218, v218, v243
	v_fmac_f32_e32 v184, v218, v56
	v_mul_f32_e32 v219, v219, v243
	v_fmac_f32_e32 v185, v219, v57
	v_mul_f32_e32 v220, v220, v243
	v_fmac_f32_e32 v186, v220, v58
	v_mul_f32_e32 v221, v221, v243
	v_fmac_f32_e32 v187, v221, v59
	v_mul_f32_e32 v222, v222, v243
	v_fmac_f32_e32 v188, v222, v60
	v_mul_f32_e32 v223, v223, v243
	v_fmac_f32_e32 v189, v223, v61
	v_mul_f32_e32 v224, v224, v243
	v_fmac_f32_e32 v190, v224, v62
	v_mul_f32_e32 v225, v225, v243
	v_fmac_f32_e32 v191, v225, v63
	v_mul_f32_e32 v226, v226, v243
	v_fmac_f32_e32 v192, v226, v64
	v_mul_f32_e32 v227, v227, v243
	v_fmac_f32_e32 v193, v227, v65
	v_mul_f32_e32 v228, v228, v243
	v_fmac_f32_e32 v194, v228, v66
	v_mul_f32_e32 v229, v229, v243
	v_fmac_f32_e32 v195, v229, v67
	v_mul_f32_e32 v230, v230, v243
	v_fmac_f32_e32 v196, v230, v68
	v_mul_f32_e32 v231, v231, v243
	v_fmac_f32_e32 v197, v231, v69
	v_mul_f32_e32 v232, v232, v243
	v_fmac_f32_e32 v198, v232, v70
	v_mul_f32_e32 v233, v233, v243
	v_fmac_f32_e32 v199, v233, v71
	v_mul_f32_e32 v234, v234, v243
	v_fmac_f32_e32 v200, v234, v72
	v_mul_f32_e32 v235, v235, v243
	v_fmac_f32_e32 v201, v235, v73
	v_mul_f32_e32 v236, v236, v243
	v_fmac_f32_e32 v202, v236, v74
	v_mul_f32_e32 v237, v237, v243
	v_fmac_f32_e32 v203, v237, v75
	s_lshl_b32 s4, s2, 13
	s_add_u32 s14, s22, s4
	s_addc_u32 s15, s23, 0
	global_store_dwordx4 v1, v[172:175], s[14:15]
	global_store_dwordx4 v1, v[176:179], s[14:15] offset:16
	global_store_dwordx4 v1, v[180:183], s[14:15] offset:2048
	global_store_dwordx4 v1, v[184:187], s[14:15] offset:2064
	global_store_dwordx4 v2, v[188:191], s[14:15]
	global_store_dwordx4 v2, v[192:195], s[14:15] offset:16
	global_store_dwordx4 v2, v[196:199], s[14:15] offset:2048
	global_store_dwordx4 v2, v[200:203], s[14:15] offset:2064
	s_mov_b32 s2, s29
	s_cmp_ge_u32 s2, 0x2080
	s_cbranch_scc0 .Lp10_A
